# wave 1 issues an early L2 writeback hint when its workgroup reaches a grid barrier (+peel, chain waits, merge/epi)
# baseline (speedup 1.0000x reference)
; #define GAS __attribute__((address_space(1)))
; __device__ __forceinline__ int lane_id() { unsigned z = 0u; asm volatile("" : "+v"(z)); return (int)__builtin_amdgcn_mbcnt_hi(~0u, __builtin_amdgcn_mbcnt_lo(~0u, z)); }
; __device__ __forceinline__ unsigned xb_add(GAS unsigned* p, unsigned v) { return __hip_atomic_fetch_add(p, v, __ATOMIC_RELAXED, __HIP_MEMORY_SCOPE_AGENT); }
; __device__ __forceinline__ void xcd_barrier(const XcdBarrier& b, int wave) {
;     asm volatile("s_waitcnt vmcnt(0)" ::: "memory");
;     __syncthreads();
;     if (wave == 0 && lane_id() == 0) {
;         GAS unsigned* bar = b.bar;
;         __builtin_amdgcn_s_waitcnt(0);
;         unsigned nloc = b.st[0], nx = b.st[1];
;         if (nloc == 0u) { xcd_barrier_complete(bar, b.x, nloc, nx); b.st[0] = nloc; b.st[1] = nx; }
;         const unsigned old = xb_add(&bar[XB_XSUB(b.x)], 1u);
.LBB0_125:
	v_writelane_b32 v240, s36, 8
	v_readlane_b32 s12, v243, 7
	v_readlane_b32 s13, v243, 8
	v_writelane_b32 v240, s37, 9
	v_writelane_b32 v240, s52, 10
	s_and_b64 s[8:9], s[52:53], s[8:9]
	s_and_b64 s[12:13], s[24:25], s[12:13]
	s_and_b64 s[8:9], s[8:9], s[12:13]
	v_cndmask_b32_e64 v0, 0, 1, s[10:11]
	s_andn2_b64 vcc, exec, s[8:9]
	v_cmp_ne_u32_e64 s[54:55], 1, v0
	v_writelane_b32 v240, s53, 11
	s_cbranch_vccnz .LBB0_172
	s_waitcnt vmcnt(0)
	s_and_b64 vcc, exec, s[54:55]
	s_barrier
	v_readlane_b32 s98, v241, 21
	s_nop 0
	s_cmp_eq_u32 s98, 64
	s_cbranch_scc0 .Lwb_0
	buffer_wbl2 sc1
.Lwb_0:
	s_cbranch_vccnz .LBB0_171
	v_mov_b32_e32 v0, v173
	s_nop 0
	v_mbcnt_lo_u32_b32 v0, -1, v0
	v_mbcnt_hi_u32_b32 v0, -1, v0
	v_cmp_eq_u32_e32 vcc, 0, v0
	s_and_saveexec_b64 s[8:9], vcc
	s_cbranch_execz .LBB0_170
	v_readlane_b32 s12, v243, 2
	s_waitcnt vmcnt(0) expcnt(0) lgkmcnt(0)
	s_nop 0
	v_mov_b32_e32 v0, s12
	ds_read_b32 v2, v0
	ds_read_b32 v0, v0 offset:4
	s_waitcnt lgkmcnt(1)
	v_cmp_ne_u32_e32 vcc, 0, v2
	s_cbranch_vccnz .LBB0_141
	v_readlane_b32 s14, v243, 0
	v_readlane_b32 s15, v243, 1
	s_load_dwordx2 s[12:13], s[14:15], 0x4
	s_waitcnt lgkmcnt(0)
	s_mul_i32 s12, s12, s2
	s_mul_i32 s12, s12, s13
	s_mov_b32 s13, 1
	s_branch .LBB0_131

; #define GAS __attribute__((address_space(1)))
; __device__ __forceinline__ int lane_id() { unsigned z = 0u; asm volatile("" : "+v"(z)); return (int)__builtin_amdgcn_mbcnt_hi(~0u, __builtin_amdgcn_mbcnt_lo(~0u, z)); }
; __device__ __forceinline__ unsigned xb_add(GAS unsigned* p, unsigned v) { return __hip_atomic_fetch_add(p, v, __ATOMIC_RELAXED, __HIP_MEMORY_SCOPE_AGENT); }
; __device__ __forceinline__ void xcd_barrier(const XcdBarrier& b, int wave) {
;     asm volatile("s_waitcnt vmcnt(0)" ::: "memory");
;     __syncthreads();
;     if (wave == 0 && lane_id() == 0) {
;         GAS unsigned* bar = b.bar;
;         __builtin_amdgcn_s_waitcnt(0);
;         unsigned nloc = b.st[0], nx = b.st[1];
;         if (nloc == 0u) { xcd_barrier_complete(bar, b.x, nloc, nx); b.st[0] = nloc; b.st[1] = nx; }
;         const unsigned old = xb_add(&bar[XB_XSUB(b.x)], 1u);
.LBB0_504:
	v_readlane_b32 s8, v240, 7
	s_add_i32 s12, s8, 3
	s_cmp_ge_i32 s12, s65
	s_cbranch_scc1 .LBB0_551
	s_waitcnt vmcnt(0)
	s_and_b64 vcc, exec, s[54:55]
	s_waitcnt vmcnt(0)
	s_barrier
	v_readlane_b32 s98, v241, 21
	s_nop 0
	s_cmp_eq_u32 s98, 64
	s_cbranch_scc0 .Lwb_1
	buffer_wbl2 sc1
.Lwb_1:
	s_cbranch_vccnz .LBB0_550
	v_mov_b32_e32 v0, v173
	s_nop 0
	v_mbcnt_lo_u32_b32 v0, -1, v0
	v_mbcnt_hi_u32_b32 v0, -1, v0
	v_cmp_eq_u32_e32 vcc, 0, v0
	s_and_saveexec_b64 s[8:9], vcc
	s_cbranch_execz .LBB0_549
	v_readlane_b32 s13, v243, 2
	s_waitcnt vmcnt(0) expcnt(0) lgkmcnt(0)
	s_nop 0
	v_mov_b32_e32 v0, s13
	ds_read_b32 v2, v0
	ds_read_b32 v1, v0 offset:4
	s_waitcnt lgkmcnt(1)
	v_cmp_ne_u32_e32 vcc, 0, v2
	s_cbranch_vccnz .LBB0_520
	v_readlane_b32 s16, v243, 0
	v_readlane_b32 s17, v243, 1
	s_load_dwordx2 s[14:15], s[16:17], 0x4
	s_waitcnt lgkmcnt(0)
	s_mul_i32 s13, s14, s2
	s_mul_i32 s13, s13, s15
	s_mov_b32 s14, 1
	s_branch .LBB0_510

; #define GAS __attribute__((address_space(1)))
; __device__ __forceinline__ int lane_id() { unsigned z = 0u; asm volatile("" : "+v"(z)); return (int)__builtin_amdgcn_mbcnt_hi(~0u, __builtin_amdgcn_mbcnt_lo(~0u, z)); }
; __device__ __forceinline__ unsigned xb_add(GAS unsigned* p, unsigned v) { return __hip_atomic_fetch_add(p, v, __ATOMIC_RELAXED, __HIP_MEMORY_SCOPE_AGENT); }
; __device__ __forceinline__ void xcd_barrier(const XcdBarrier& b, int wave) {
;     asm volatile("s_waitcnt vmcnt(0)" ::: "memory");
;     __syncthreads();
;     if (wave == 0 && lane_id() == 0) {
;         GAS unsigned* bar = b.bar;
;         __builtin_amdgcn_s_waitcnt(0);
;         unsigned nloc = b.st[0], nx = b.st[1];
;         if (nloc == 0u) { xcd_barrier_complete(bar, b.x, nloc, nx); b.st[0] = nloc; b.st[1] = nx; }
;         const unsigned old = xb_add(&bar[XB_XSUB(b.x)], 1u);
.LBB0_881:
	v_readlane_b32 s8, v240, 7
	v_readlane_b32 s64, v241, 59
	s_add_i32 s14, s8, 4
	v_readlane_b32 s65, v241, 60
	s_cmp_ge_i32 s14, s65
	s_cbranch_scc1 .LBB0_894
	s_waitcnt vmcnt(0)
	v_readlane_b32 s72, v241, 63
	s_and_b64 vcc, exec, s[54:55]
	v_readlane_b32 s66, v241, 61
	v_readlane_b32 s73, v240, 0
	s_waitcnt vmcnt(0) lgkmcnt(0)
	s_barrier
	v_readlane_b32 s67, v241, 62
	v_readlane_b32 s98, v241, 21
	s_nop 0
	s_cmp_eq_u32 s98, 64
	s_cbranch_scc0 .Lwb_2
	buffer_wbl2 sc1
.Lwb_2:
	s_cbranch_vccnz .LBB0_928
	v_mov_b32_e32 v0, v173
	s_nop 0
	v_mbcnt_lo_u32_b32 v0, -1, v0
	v_mbcnt_hi_u32_b32 v0, -1, v0
	v_cmp_eq_u32_e32 vcc, 0, v0
	s_and_saveexec_b64 s[8:9], vcc
	s_cbranch_execz .LBB0_927
	v_readlane_b32 s12, v243, 2
	s_waitcnt vmcnt(0) expcnt(0) lgkmcnt(0)
	v_readlane_b32 s26, v240, 1
	v_mov_b32_e32 v0, s12
	ds_read_b32 v2, v0
	ds_read_b32 v1, v0 offset:4
	v_readlane_b32 s27, v240, 2
	s_waitcnt lgkmcnt(1)
	v_cmp_ne_u32_e32 vcc, 0, v2
	s_cbranch_vccnz .LBB0_898
	v_readlane_b32 s16, v243, 0
	v_readlane_b32 s17, v243, 1
	s_load_dwordx2 s[12:13], s[16:17], 0x4
	s_mov_b32 s20, 1
	s_waitcnt lgkmcnt(0)
	s_mul_i32 s15, s12, s2
	s_mul_i32 s15, s15, s13
	s_branch .LBB0_887

; #define GAS __attribute__((address_space(1)))
; __device__ __forceinline__ int lane_id() { unsigned z = 0u; asm volatile("" : "+v"(z)); return (int)__builtin_amdgcn_mbcnt_hi(~0u, __builtin_amdgcn_mbcnt_lo(~0u, z)); }
; __device__ __forceinline__ unsigned xb_add(GAS unsigned* p, unsigned v) { return __hip_atomic_fetch_add(p, v, __ATOMIC_RELAXED, __HIP_MEMORY_SCOPE_AGENT); }
; __device__ __forceinline__ void xcd_barrier(const XcdBarrier& b, int wave) {
;     asm volatile("s_waitcnt vmcnt(0)" ::: "memory");
;     __syncthreads();
;     if (wave == 0 && lane_id() == 0) {
;         GAS unsigned* bar = b.bar;
;         __builtin_amdgcn_s_waitcnt(0);
;         unsigned nloc = b.st[0], nx = b.st[1];
;         if (nloc == 0u) { xcd_barrier_complete(bar, b.x, nloc, nx); b.st[0] = nloc; b.st[1] = nx; }
;         const unsigned old = xb_add(&bar[XB_XSUB(b.x)], 1u);
.LBB0_1070:
	v_readlane_b32 s8, v240, 7
	s_add_i32 s14, s8, 5
	s_cmp_ge_i32 s14, s65
	s_cbranch_scc1 .LBB0_1117
	s_waitcnt vmcnt(0)
	s_and_b64 vcc, exec, s[54:55]
	s_barrier
	v_readlane_b32 s98, v241, 21
	s_nop 0
	s_cmp_eq_u32 s98, 64
	s_cbranch_scc0 .Lwb_3
	buffer_wbl2 sc1
.Lwb_3:
	s_cbranch_vccnz .LBB0_1116
	v_mov_b32_e32 v0, v173
	s_nop 0
	v_mbcnt_lo_u32_b32 v0, -1, v0
	v_mbcnt_hi_u32_b32 v0, -1, v0
	v_cmp_eq_u32_e32 vcc, 0, v0
	s_and_saveexec_b64 s[8:9], vcc
	s_cbranch_execz .LBB0_1115
	v_readlane_b32 s12, v243, 2
	s_waitcnt vmcnt(0) expcnt(0) lgkmcnt(0)
	s_nop 0
	v_mov_b32_e32 v0, s12
	ds_read_b32 v2, v0
	ds_read_b32 v1, v0 offset:4
	s_waitcnt lgkmcnt(1)
	v_cmp_ne_u32_e32 vcc, 0, v2
	s_cbranch_vccnz .LBB0_1086
	v_readlane_b32 s16, v243, 0
	v_readlane_b32 s17, v243, 1
	s_load_dwordx2 s[12:13], s[16:17], 0x4
	s_mov_b32 s20, 1
	s_waitcnt lgkmcnt(0)
	s_mul_i32 s15, s12, s2
	s_mul_i32 s15, s15, s13
	s_branch .LBB0_1076

; #define GAS __attribute__((address_space(1)))
; __device__ __forceinline__ int lane_id() { unsigned z = 0u; asm volatile("" : "+v"(z)); return (int)__builtin_amdgcn_mbcnt_hi(~0u, __builtin_amdgcn_mbcnt_lo(~0u, z)); }
; __device__ __forceinline__ unsigned xb_add(GAS unsigned* p, unsigned v) { return __hip_atomic_fetch_add(p, v, __ATOMIC_RELAXED, __HIP_MEMORY_SCOPE_AGENT); }
; __device__ __forceinline__ void xcd_barrier(const XcdBarrier& b, int wave) {
;     asm volatile("s_waitcnt vmcnt(0)" ::: "memory");
;     __syncthreads();
;     if (wave == 0 && lane_id() == 0) {
;         GAS unsigned* bar = b.bar;
;         __builtin_amdgcn_s_waitcnt(0);
;         unsigned nloc = b.st[0], nx = b.st[1];
;         if (nloc == 0u) { xcd_barrier_complete(bar, b.x, nloc, nx); b.st[0] = nloc; b.st[1] = nx; }
;         const unsigned old = xb_add(&bar[XB_XSUB(b.x)], 1u);
; __global__ void __launch_bounds__(512, 2) mega_fwd(Params p) {
;     ...
;         if (IN(pb + 4)) { combine_merge(F); xcd_barrier(bar, F.wave);
.LBB0_1126:
	s_waitcnt vmcnt(0)
	s_and_b64 vcc, exec, s[54:55]
	s_waitcnt vmcnt(0) lgkmcnt(0)
	s_barrier
	v_readlane_b32 s98, v241, 21
	s_nop 0
	s_cmp_eq_u32 s98, 64
	s_cbranch_scc0 .Lwb_4
	buffer_wbl2 sc1
.Lwb_4:
	s_cbranch_vccnz .LBB0_1171
	v_mov_b32_e32 v0, v173
	s_nop 0
	v_mbcnt_lo_u32_b32 v0, -1, v0
	v_mbcnt_hi_u32_b32 v0, -1, v0
	v_cmp_eq_u32_e32 vcc, 0, v0
	s_and_saveexec_b64 s[8:9], vcc
	s_cbranch_execz .LBB0_1170
	v_readlane_b32 s12, v243, 2
	s_waitcnt vmcnt(0) expcnt(0) lgkmcnt(0)
	s_nop 0
	v_mov_b32_e32 v0, s12
	ds_read_b32 v2, v0
	ds_read_b32 v1, v0 offset:4
	s_waitcnt lgkmcnt(1)
	v_cmp_ne_u32_e32 vcc, 0, v2
	s_cbranch_vccnz .LBB0_1141
	v_readlane_b32 s14, v243, 0
	v_readlane_b32 s15, v243, 1
	s_load_dwordx2 s[12:13], s[14:15], 0x4
	s_mov_b32 s15, 1
	s_waitcnt lgkmcnt(0)
	s_mul_i32 s14, s12, s2
	s_mul_i32 s14, s14, s13
	s_branch .LBB0_1131

; #define GAS __attribute__((address_space(1)))
; __device__ __forceinline__ int lane_id() { unsigned z = 0u; asm volatile("" : "+v"(z)); return (int)__builtin_amdgcn_mbcnt_hi(~0u, __builtin_amdgcn_mbcnt_lo(~0u, z)); }
; __device__ __forceinline__ unsigned xb_add(GAS unsigned* p, unsigned v) { return __hip_atomic_fetch_add(p, v, __ATOMIC_RELAXED, __HIP_MEMORY_SCOPE_AGENT); }
; __device__ __forceinline__ void xcd_barrier(const XcdBarrier& b, int wave) {
;     asm volatile("s_waitcnt vmcnt(0)" ::: "memory");
;     __syncthreads();
;     if (wave == 0 && lane_id() == 0) {
;         GAS unsigned* bar = b.bar;
;         __builtin_amdgcn_s_waitcnt(0);
;         unsigned nloc = b.st[0], nx = b.st[1];
;         if (nloc == 0u) { xcd_barrier_complete(bar, b.x, nloc, nx); b.st[0] = nloc; b.st[1] = nx; }
;         const unsigned old = xb_add(&bar[XB_XSUB(b.x)], 1u);
; __global__ void __launch_bounds__(512, 2) mega_fwd(Params p) {
;     ...
;             xcd_barrier(bar, F.wave); if (l == DEPTH - 1) combine_out(F, 1);
.LBB0_1282:
	s_waitcnt vmcnt(0)
	s_and_b64 vcc, exec, s[54:55]
	s_waitcnt vmcnt(0)
	s_barrier
	v_readlane_b32 s98, v241, 21
	s_nop 0
	s_cmp_eq_u32 s98, 64
	s_cbranch_scc0 .Lwb_5
	buffer_wbl2 sc1
.Lwb_5:
	s_cbranch_vccnz .LBB0_1327
	v_mov_b32_e32 v0, v173
	s_nop 0
	v_mbcnt_lo_u32_b32 v0, -1, v0
	v_mbcnt_hi_u32_b32 v0, -1, v0
	v_cmp_eq_u32_e32 vcc, 0, v0
	s_and_saveexec_b64 s[8:9], vcc
	s_cbranch_execz .LBB0_1326
	v_readlane_b32 s12, v243, 2
	s_waitcnt vmcnt(0) expcnt(0) lgkmcnt(0)
	s_nop 0
	v_mov_b32_e32 v0, s12
	ds_read_b32 v2, v0
	ds_read_b32 v1, v0 offset:4
	s_waitcnt lgkmcnt(1)
	v_cmp_ne_u32_e32 vcc, 0, v2
	s_cbranch_vccnz .LBB0_1297
	v_readlane_b32 s14, v243, 0
	v_readlane_b32 s15, v243, 1
	s_load_dwordx2 s[12:13], s[14:15], 0x4
	s_mov_b32 s24, 1
	s_waitcnt lgkmcnt(0)
	s_mul_i32 s20, s12, s2
	s_mul_i32 s20, s20, s13
	s_branch .LBB0_1287
